# HGRN A/B: packed v_pk_mul_f32 on the state accumulators split into scalar v_mul_f32 before the MFMAs; ds_read2_b64 fragment reads split into ds_read_b64 pairs (on top of v23)
# speedup vs baseline: 1.0059x; 1.0059x over previous
; __device__ __forceinline__ void hgrn_a(unsigned char* lds, const Params& p, int jl, bf16_t* proj, bf16_t* mix, float* dbuf, bf16_t* scr, float* useg, float* dseg, int blk, int G, int tid) {
;     ...
;             const int tt = w & 3, vh = w >> 2;
;             f32x4 pm[4];
;             __builtin_amdgcn_sched_barrier(0);
;             { bf16x8 qfr[4];
; #pragma unroll
;               for (int k4 = 0; k4 < 4; ++k4) qfr[k4] = *(const bf16x8*)(QT + (tt * 16 + fr) * 136 + k4 * 32 + fq * 8);
; #pragma unroll
;               for (int sh = 0; sh < 2; ++sh) { bf16x8 kfr[2][4];
; #pragma unroll
;                   for (int s2 = 0; s2 < 2; ++s2)
; #pragma unroll
;                       for (int k4 = 0; k4 < 4; ++k4) kfr[s2][k4] = *(const bf16x8*)(KTL + ((sh * 2 + s2) * 16 + fr) * 136 + k4 * 32 + fq * 8);
;                   __builtin_amdgcn_sched_barrier(0);
; #pragma unroll
;                   for (int s2 = 0; s2 < 2; ++s2) { const int st = sh * 2 + s2; pm[st] = (f32x4){0.f, 0.f, 0.f, 0.f};
; #pragma unroll
;                       for (int k4 = 0; k4 < 4; ++k4) pm[st] = MFMA16(kfr[s2][k4], qfr[k4], pm[st]);
; #pragma unroll
;                       for (int j = 0; j < 4; ++j) { const bool keep = (st < tt) || (st == tt && fq * 4 + j <= fr); pm[st][j] = keep ? pm[st][j] : 0.f; } }
;                   __builtin_amdgcn_sched_barrier(0); } }
;             bf16x8 pb[2]; pb[0] = pack8(pm[0], pm[1]); pb[1] = pack8(pm[2], pm[3]);
;             f32x4 oo[4];
;             { bf16x8 vfr[4][2];
; #pragma unroll
;               for (int vt = 0; vt < 4; ++vt)
; #pragma unroll
;                   for (int k2 = 0; k2 < 2; ++k2) { const bf16_t* vp = VTL + ((vh * 4 + vt) * 16 + fr) * 72 + k2 * 32 + fq * 4; vfr[vt][k2] = cat8(*(const bf16x4*)vp, *(const bf16x4*)(vp + 16)); }
;               __builtin_amdgcn_sched_barrier(0);
; #pragma unroll
;               for (int vt = 0; vt < 4; ++vt) { oo[vt] = (f32x4){0.f, 0.f, 0.f, 0.f};
; #pragma unroll
;                   for (int k2 = 0; k2 < 2; ++k2) oo[vt] = MFMA16(vfr[vt][k2], pb[k2], oo[vt]); } }
;             { const int tok = tt * 16 + fr;
;               if (tok < nvalid) { bf16_t* mp = mix + (size_t)(row0 + tok) * DM + h * 128 + vh * 64 + fq * 4;
; #pragma unroll
;                   for (int vt = 0; vt < 4; ++vt) *(u32x2*)(mp + vt * 16) = pack4(oo[vt]); } }
.LBB0_255:
	s_or_b64 exec, exec, s[24:25]
	s_waitcnt lgkmcnt(0)
	s_barrier
	ds_read_b128 v[58:61], v160 offset:34816
	ds_read_b128 v[62:65], v160 offset:34880
	ds_read_b128 v[66:69], v160 offset:34944
	ds_read_b128 v[70:73], v160 offset:35008
	ds_read_b128 v[170:173], v161 offset:52224
	ds_read_b128 v[174:177], v161 offset:52288
	ds_read_b128 v[178:181], v161 offset:52352
	ds_read_b128 v[182:185], v161 offset:52416
	ds_read_b128 v[186:189], v161 offset:56576
	ds_read_b128 v[190:193], v161 offset:56640
	ds_read_b128 v[194:197], v161 offset:56704
	ds_read_b128 v[198:201], v161 offset:56768
	s_waitcnt lgkmcnt(7)
	v_mfma_f32_16x16x32_bf16 v[170:173], v[170:173], v[58:61], 0
	s_waitcnt lgkmcnt(6)
	v_mfma_f32_16x16x32_bf16 v[170:173], v[174:177], v[62:65], v[170:173]
	s_waitcnt lgkmcnt(3)
	v_mfma_f32_16x16x32_bf16 v[174:177], v[186:189], v[58:61], 0
	v_mfma_f32_16x16x32_bf16 v[170:173], v[178:181], v[66:69], v[170:173]
	s_waitcnt lgkmcnt(2)
	v_mfma_f32_16x16x32_bf16 v[174:177], v[190:193], v[62:65], v[174:177]
	v_mfma_f32_16x16x32_bf16 v[170:173], v[182:185], v[70:73], v[170:173]
	s_waitcnt lgkmcnt(1)
	v_mfma_f32_16x16x32_bf16 v[174:177], v[194:197], v[66:69], v[174:177]
	s_nop 5
	v_cndmask_b32_e64 v127, 0, v170, s[44:45]
	v_cndmask_b32_e64 v129, 0, v171, s[46:47]
	v_cndmask_b32_e64 v131, 0, v172, s[48:49]
	v_cndmask_b32_e64 v133, 0, v173, s[50:51]
	s_waitcnt lgkmcnt(0)
	v_mfma_f32_16x16x32_bf16 v[170:173], v[198:201], v[70:73], v[174:177]
	s_nop 7
	v_cndmask_b32_e64 v135, 0, v170, s[52:53]
	v_cndmask_b32_e64 v137, 0, v171, s[54:55]
	v_cndmask_b32_e64 v152, 0, v172, s[56:57]
	v_cndmask_b32_e64 v153, 0, v173, s[58:59]
	ds_read_b128 v[170:173], v161 offset:60928
	ds_read_b128 v[174:177], v161 offset:60992
	ds_read_b128 v[178:181], v161 offset:61056
	ds_read_b128 v[182:185], v161 offset:61120
	ds_read_b128 v[186:189], v161 offset:65280
	ds_read_b128 v[190:193], v161 offset:65344
	ds_read_b128 v[194:197], v161 offset:65408
	ds_read_b128 v[198:201], v161 offset:65472
	s_waitcnt lgkmcnt(7)
	v_mfma_f32_16x16x32_bf16 v[170:173], v[170:173], v[58:61], 0
	v_readlane_b32 s24, v255, 38
	v_readlane_b32 s25, v255, 39
	s_waitcnt lgkmcnt(3)
	v_mfma_f32_16x16x32_bf16 v[58:61], v[186:189], v[58:61], 0
	s_waitcnt lgkmcnt(2)
	v_mfma_f32_16x16x32_bf16 v[58:61], v[190:193], v[62:65], v[58:61]
	v_mfma_f32_16x16x32_bf16 v[170:173], v[174:177], v[62:65], v[170:173]
	s_waitcnt lgkmcnt(1)
	v_mfma_f32_16x16x32_bf16 v[58:61], v[194:197], v[66:69], v[58:61]
	v_mfma_f32_16x16x32_bf16 v[170:173], v[178:181], v[66:69], v[170:173]
	s_waitcnt lgkmcnt(0)
	v_mfma_f32_16x16x32_bf16 v[58:61], v[198:201], v[70:73], v[58:61]
	v_mfma_f32_16x16x32_bf16 v[170:173], v[182:185], v[70:73], v[170:173]
	s_nop 6
	v_cndmask_b32_e64 v66, v58, 0, s[24:25]
	v_readlane_b32 s24, v255, 40
	v_readlane_b32 s25, v255, 41
	v_cndmask_b32_e64 v62, 0, v170, s[60:61]
	v_cndmask_b32_e64 v63, 0, v171, s[62:63]
	v_cndmask_b32_e64 v64, 0, v172, s[64:65]
	v_cndmask_b32_e64 v65, 0, v173, s[66:67]
	v_cndmask_b32_e64 v67, v59, 0, s[24:25]
	v_cndmask_b32_e64 v68, v60, 0, s[18:19]
	v_cndmask_b32_e64 v69, v61, 0, s[20:21]
	v_add_u32_e32 v70, 0x800, v162
	v_cvt_pk_bf16_f32 v170, v62, v63
	v_cvt_pk_bf16_f32 v171, v64, v65
	v_cvt_pk_bf16_f32 v172, v66, v67
	v_cvt_pk_bf16_f32 v173, v68, v69
	ds_read_b64 v[62:63], v162
	ds_read_b64 v[64:65], v162 offset:32
	ds_read_b64 v[66:67], v162 offset:64
	ds_read_b64 v[68:69], v162 offset:96
	ds_read_b64 v[174:175], v70 offset:256
	ds_read_b64 v[176:177], v70 offset:288
	ds_read_b64 v[178:179], v70 offset:320
	ds_read_b64 v[180:181], v70 offset:352
	v_add_u32_e32 v70, 0x1000, v162
	ds_read_b64 v[182:183], v70 offset:512
	ds_read_b64 v[184:185], v70 offset:544
	ds_read_b64 v[186:187], v70 offset:576
	ds_read_b64 v[188:189], v70 offset:608
	v_add_u32_e32 v70, 0x1800, v162
	ds_read_b64 v[190:191], v70 offset:768
	ds_read_b64 v[192:193], v70 offset:800
	v_cvt_pk_bf16_f32 v58, v127, v129
	v_cvt_pk_bf16_f32 v59, v131, v133
	v_cvt_pk_bf16_f32 v60, v135, v137
	v_cvt_pk_bf16_f32 v61, v152, v153
	s_waitcnt lgkmcnt(12)
	ds_read_b64 v[194:195], v70 offset:832
	ds_read_b64 v[196:197], v70 offset:864
	s_nop 0
	v_mfma_f32_16x16x32_bf16 v[62:65], v[62:65], v[58:61], 0
	s_waitcnt lgkmcnt(12)
	v_mfma_f32_16x16x32_bf16 v[70:73], v[66:69], v[170:173], v[62:65]
	s_waitcnt lgkmcnt(10)
	v_mfma_f32_16x16x32_bf16 v[62:65], v[174:177], v[58:61], 0
	s_waitcnt lgkmcnt(8)
	v_mfma_f32_16x16x32_bf16 v[66:69], v[178:181], v[170:173], v[62:65]
	s_waitcnt lgkmcnt(6)
	v_mfma_f32_16x16x32_bf16 v[62:65], v[182:185], v[58:61], 0
	s_waitcnt lgkmcnt(2)
	v_mfma_f32_16x16x32_bf16 v[58:61], v[190:193], v[58:61], 0
	v_mfma_f32_16x16x32_bf16 v[62:65], v[186:189], v[170:173], v[62:65]
	s_waitcnt lgkmcnt(0)
	v_mfma_f32_16x16x32_bf16 v[58:61], v[194:197], v[170:173], v[58:61]
	s_and_saveexec_b64 s[24:25], s[74:75]
	s_cbranch_execz .LBB0_257
	v_add_u32_e32 v152, s15, v101
	v_ashrrev_i32_e32 v153, 31, v152
	v_lshlrev_b64 v[152:153], 12, v[152:153]
	v_lshl_add_u64 v[152:153], v[140:141], 0, v[152:153]
	v_cvt_pk_bf16_f32 v70, v70, v71
	v_cvt_pk_bf16_f32 v71, v72, v73
	v_cvt_pk_bf16_f32 v66, v66, v67
	v_cvt_pk_bf16_f32 v67, v68, v69
	v_cvt_pk_bf16_f32 v62, v62, v63
	v_cvt_pk_bf16_f32 v63, v64, v65
	v_cvt_pk_bf16_f32 v58, v58, v59
	v_cvt_pk_bf16_f32 v59, v60, v61
	global_store_dwordx2 v[152:153], v[70:71], off
	global_store_dwordx2 v[152:153], v[66:67], off offset:32
	global_store_dwordx2 v[152:153], v[62:63], off offset:64
	global_store_dwordx2 v[152:153], v[58:59], off offset:96
; #define MFMA16(a, b, c) __builtin_amdgcn_mfma_f32_16x16x32_bf16((a), (b), (c), 0, 0, 0)
; __device__ __forceinline__ void hgrn_a(unsigned char* lds, const Params& p, int jl, bf16_t* proj, bf16_t* mix, float* dbuf, bf16_t* scr, float* useg, float* dseg, int blk, int G, int tid) {
;     ...
;             for (int i = 0; i < 2; ++i) { const int cidx = tid + 512 * i, v = cidx >> 3, sc = cidx & 7; const bf16x8 x = *(const bf16x8*)(VTL + v * 72 + sc * 8);
;                 *(bf16x8*)(vd + (size_t)(v >> 1) * dstride + (v & 1) * 64 + sc * 8) = x; }
;             __builtin_amdgcn_sched_barrier(0);
;             if (!samp) { bf16x8 vb[2];
; #pragma unroll
;                 for (int ks = 0; ks < 2; ++ks) vb[ks] = *(const bf16x8*)(VTL + (w * 16 + fr) * 72 + ks * 32 + fq * 8);
; #pragma unroll
;                 for (int kh2 = 0; kh2 < 2; ++kh2) { bf16x8 kf[4][2]; f32x4 dv[4];
; #pragma unroll
;                     for (int k3 = 0; k3 < 4; ++k3) { dv[k3] = *(const f32x4*)(DLS + (kh2 * 4 + k3) * 16 + fq * 4);
; #pragma unroll
;                         for (int ks = 0; ks < 2; ++ks) kf[k3][ks] = *(const bf16x8*)(KHT + ((kh2 * 4 + k3) * 16 + fr) * 72 + ks * 32 + fq * 8); }
;                     __builtin_amdgcn_sched_barrier(0);
; #pragma unroll
;                     for (int k3 = 0; k3 < 4; ++k3) U[kh2 * 4 + k3] = U[kh2 * 4 + k3] * dv[k3];
; #pragma unroll
;                     for (int ks = 0; ks < 2; ++ks)
; #pragma unroll
;                         for (int k3 = 0; k3 < 4; ++k3) U[kh2 * 4 + k3] = MFMA16(kf[k3][ks], vb[ks], U[kh2 * 4 + k3]);
;                     __builtin_amdgcn_sched_barrier(0); } }
.LBB0_257:
	s_or_b64 exec, exec, s[24:25]
	s_nop 4
	ds_read_b128 v[58:61], v163
	v_mad_i64_i32 v[62:63], s[24:25], s30, v76, 0
	v_lshl_add_u64 v[62:63], v[62:63], 1, s[26:27]
	v_lshl_add_u64 v[62:63], v[62:63], 0, v[0:1]
	v_mov_b32_e32 v131, v1
	v_lshl_add_u64 v[62:63], v[62:63], 0, v[130:131]
	s_waitcnt lgkmcnt(0)
	global_store_dwordx4 v[62:63], v[58:61], off
	ds_read_b128 v[58:61], v164
	v_mad_i64_i32 v[62:63], s[24:25], s30, v124, 0
	v_lshl_add_u64 v[62:63], v[62:63], 1, s[26:27]
	v_mov_b32_e32 v133, v1
	v_lshl_add_u64 v[62:63], v[62:63], 0, v[132:133]
	v_lshl_add_u64 v[62:63], v[62:63], 0, v[130:131]
	s_waitcnt lgkmcnt(0)
	global_store_dwordx4 v[62:63], v[58:61], off
	s_and_b64 vcc, exec, s[10:11]
	s_cbranch_vccnz .LBB0_242
	ds_read_b128 v[58:61], v165
	ds_read_b128 v[62:65], v165 offset:64
	v_add_u32_e32 v127, 0x1a800, v103
	ds_read_b128 v[66:69], v166
	ds_read_b128 v[70:73], v166 offset:64
	ds_read_b128 v[170:173], v127
	ds_read_b128 v[174:177], v127 offset:64
	ds_read_b128 v[178:181], v166 offset:2304
	ds_read_b128 v[182:185], v166 offset:2368
	ds_read_b128 v[186:189], v166 offset:4608
	ds_read_b128 v[190:193], v166 offset:4672
	ds_read_b128 v[194:197], v127 offset:128
	ds_read_b128 v[198:201], v127 offset:192
	ds_read_b128 v[202:205], v166 offset:6912
	ds_read_b128 v[216:219], v166 offset:6976
	s_waitcnt lgkmcnt(9)
	v_mul_f32_e32 v56, v56, v172
	v_mul_f32_e32 v57, v57, v173
	v_mul_f32_e32 v54, v54, v170
	v_mul_f32_e32 v55, v55, v171
	s_waitcnt lgkmcnt(8)
	v_mul_f32_e32 v44, v44, v176
	v_mul_f32_e32 v45, v45, v177
	v_mul_f32_e32 v42, v42, v174
	v_mul_f32_e32 v43, v43, v175
	s_waitcnt lgkmcnt(3)
	v_mul_f32_e32 v36, v36, v196
	v_mul_f32_e32 v37, v37, v197
	v_mul_f32_e32 v34, v34, v194
	v_mul_f32_e32 v35, v35, v195
	s_waitcnt lgkmcnt(2)
	v_mul_f32_e32 v32, v32, v200
	v_mul_f32_e32 v33, v33, v201
	v_mul_f32_e32 v30, v30, v198
	v_mul_f32_e32 v31, v31, v199
	v_mfma_f32_16x16x32_bf16 v[54:57], v[66:69], v[58:61], v[54:57]
	v_mfma_f32_16x16x32_bf16 v[42:45], v[178:181], v[58:61], v[42:45]
	v_mfma_f32_16x16x32_bf16 v[34:37], v[186:189], v[58:61], v[34:37]
	s_waitcnt lgkmcnt(1)
	v_mfma_f32_16x16x32_bf16 v[30:33], v[202:205], v[58:61], v[30:33]
	v_mfma_f32_16x16x32_bf16 v[54:57], v[70:73], v[62:65], v[54:57]
	v_mfma_f32_16x16x32_bf16 v[42:45], v[182:185], v[62:65], v[42:45]
	v_mfma_f32_16x16x32_bf16 v[34:37], v[190:193], v[62:65], v[34:37]
	s_waitcnt lgkmcnt(0)
	v_mfma_f32_16x16x32_bf16 v[30:33], v[216:219], v[62:65], v[30:33]
	ds_read_b128 v[66:69], v166 offset:9216
	ds_read_b128 v[70:73], v166 offset:9280
	ds_read_b128 v[170:173], v127 offset:256
	ds_read_b128 v[174:177], v127 offset:320
	ds_read_b128 v[178:181], v166 offset:11520
	ds_read_b128 v[182:185], v166 offset:11584
	ds_read_b128 v[186:189], v166 offset:13824
	ds_read_b128 v[190:193], v166 offset:13888
	ds_read_b128 v[194:197], v127 offset:384
	ds_read_b128 v[198:201], v127 offset:448
	ds_read_b128 v[202:205], v166 offset:16128
	ds_read_b128 v[216:219], v166 offset:16192
	s_waitcnt lgkmcnt(9)
	v_mul_f32_e32 v52, v52, v172
	v_mul_f32_e32 v53, v53, v173
	v_mul_f32_e32 v50, v50, v170
	v_mul_f32_e32 v51, v51, v171
	s_waitcnt lgkmcnt(8)
	v_mul_f32_e32 v28, v28, v176
	v_mul_f32_e32 v29, v29, v177
	v_mul_f32_e32 v26, v26, v174
	v_mul_f32_e32 v27, v27, v175
	s_waitcnt lgkmcnt(3)
	v_mul_f32_e32 v24, v24, v196
	v_mul_f32_e32 v25, v25, v197
	v_mul_f32_e32 v22, v22, v194
	v_mul_f32_e32 v23, v23, v195
	s_waitcnt lgkmcnt(2)
	v_mul_f32_e32 v20, v20, v200
	v_mul_f32_e32 v21, v21, v201
	v_mul_f32_e32 v18, v18, v198
	v_mul_f32_e32 v19, v19, v199
	v_mfma_f32_16x16x32_bf16 v[50:53], v[66:69], v[58:61], v[50:53]
	v_mfma_f32_16x16x32_bf16 v[26:29], v[178:181], v[58:61], v[26:29]
	v_mfma_f32_16x16x32_bf16 v[22:25], v[186:189], v[58:61], v[22:25]
	s_waitcnt lgkmcnt(1)
	v_mfma_f32_16x16x32_bf16 v[18:21], v[202:205], v[58:61], v[18:21]
	v_mfma_f32_16x16x32_bf16 v[50:53], v[70:73], v[62:65], v[50:53]
	v_mfma_f32_16x16x32_bf16 v[26:29], v[182:185], v[62:65], v[26:29]
	v_mfma_f32_16x16x32_bf16 v[22:25], v[190:193], v[62:65], v[22:25]
	s_waitcnt lgkmcnt(0)
	v_mfma_f32_16x16x32_bf16 v[18:21], v[216:219], v[62:65], v[18:21]
	s_branch .LBB0_242

; #define MFMA16(a, b, c) __builtin_amdgcn_mfma_f32_16x16x32_bf16((a), (b), (c), 0, 0, 0)
; __device__ __forceinline__ bf16x8 pack8(f32x4 a, f32x4 b) { u32x4 w = {pk2(a[0], a[1]), pk2(a[2], a[3]), pk2(b[0], b[1]), pk2(b[2], b[3])}; return __builtin_bit_cast(bf16x8, w); }
; __device__ __forceinline__ bf16x8 cat8(bf16x4 lo, bf16x4 hi) { return __builtin_shufflevector(lo, hi, 0, 1, 2, 3, 4, 5, 6, 7); }
; __device__ __forceinline__ void hgrn_b(unsigned char* lds, const Params& p, int jl, const bf16_t* proj, bf16_t* mix, const float* dbuf, const bf16_t* scr, const float* useg, const float* dseg, int blk, int G, int tid) {
;     ...
;             const bf16_t* qh = QH + buf * (64 * 136); const bf16_t* kt = KT + buf * (128 * 72); const bf16_t* vt = VT + buf * (128 * 72); const float* dl = DL + buf * 128;
;             f32x4 oT[4];
;             { bf16x8 sa[4];
; #pragma unroll
;               for (int k2 = 0; k2 < 4; ++k2) sa[k2] = pack8(S[2 * k2], S[2 * k2 + 1]);
; #pragma unroll
;               for (int th = 0; th < 2; ++th) { bf16x8 qfr[2][4];
; #pragma unroll
;                   for (int t2 = 0; t2 < 2; ++t2)
; #pragma unroll
;                       for (int k2 = 0; k2 < 4; ++k2) { const bf16_t* qp = qh + ((th * 2 + t2) * 16 + fr) * 136 + k2 * 32 + fq * 4; qfr[t2][k2] = cat8(*(const bf16x4*)qp, *(const bf16x4*)(qp + 16)); }
;                   __builtin_amdgcn_sched_barrier(0);
; #pragma unroll
;                   for (int t2 = 0; t2 < 2; ++t2) oT[th * 2 + t2] = (f32x4){0.f, 0.f, 0.f, 0.f};
; #pragma unroll
;                   for (int k2 = 0; k2 < 4; ++k2)
; #pragma unroll
;                       for (int t2 = 0; t2 < 2; ++t2) oT[th * 2 + t2] = MFMA16(sa[k2], qfr[t2][k2], oT[th * 2 + t2]);
;                   __builtin_amdgcn_sched_barrier(0); } }
;             { bf16x8 vb[2];
; #pragma unroll
;               for (int ks = 0; ks < 2; ++ks) vb[ks] = *(const bf16x8*)(vt + (w * 16 + fr) * 72 + ks * 32 + fq * 8);
; #pragma unroll
;               for (int kh2 = 0; kh2 < 2; ++kh2) { bf16x8 kf[4][2]; f32x4 dv[4];
; #pragma unroll
;                   for (int k3 = 0; k3 < 4; ++k3) { dv[k3] = *(const f32x4*)(dl + (kh2 * 4 + k3) * 16 + fq * 4);
; #pragma unroll
;                       for (int ks = 0; ks < 2; ++ks) kf[k3][ks] = *(const bf16x8*)(kt + ((kh2 * 4 + k3) * 16 + fr) * 72 + ks * 32 + fq * 8); }
.LBB0_412:
	s_or_b64 exec, exec, s[16:17]
	s_and_b32 s19, s19, 1
	s_mul_i32 s16, s19, 0x4400
	v_add3_u32 v0, v125, s16, v180
	v_add_u32_e32 v152, 0x1000, v0
	ds_read_b64 v[68:69], v0
	ds_read_b64 v[70:71], v0 offset:32
	ds_read_b64 v[184:185], v0 offset:64
	ds_read_b64 v[186:187], v0 offset:96
	ds_read_b64 v[188:189], v0 offset:128
	ds_read_b64 v[190:191], v0 offset:160
	ds_read_b64 v[192:193], v0 offset:192
	ds_read_b64 v[194:195], v0 offset:224
	ds_read_b64 v[196:197], v152 offset:256
	ds_read_b64 v[198:199], v152 offset:288
	ds_read_b64 v[200:201], v152 offset:320
	ds_read_b64 v[202:203], v152 offset:352
	ds_read_b64 v[204:205], v152 offset:384
	ds_read_b64 v[206:207], v152 offset:416
	v_cvt_pk_bf16_f32 v72, v36, v37
	v_cvt_pk_bf16_f32 v73, v38, v39
	v_cvt_pk_bf16_f32 v74, v40, v41
	v_cvt_pk_bf16_f32 v75, v42, v43
	v_cvt_pk_bf16_f32 v76, v44, v45
	v_cvt_pk_bf16_f32 v77, v46, v47
	v_cvt_pk_bf16_f32 v78, v48, v49
	v_cvt_pk_bf16_f32 v79, v50, v51
	v_cvt_pk_bf16_f32 v166, v56, v57
	v_cvt_pk_bf16_f32 v167, v58, v59
	v_cvt_pk_bf16_f32 v164, v52, v53
	v_cvt_pk_bf16_f32 v165, v54, v55
	v_cvt_pk_bf16_f32 v220, v60, v61
	v_cvt_pk_bf16_f32 v221, v62, v63
	v_cvt_pk_bf16_f32 v222, v64, v65
	v_cvt_pk_bf16_f32 v223, v66, v67
	s_waitcnt lgkmcnt(12)
	ds_read_b64 v[216:217], v152 offset:448
	ds_read_b64 v[218:219], v152 offset:480
	v_mfma_f32_16x16x32_bf16 v[68:71], v[72:75], v[68:71], 0
	s_waitcnt lgkmcnt(6)
	v_mfma_f32_16x16x32_bf16 v[196:199], v[72:75], v[196:199], 0
	v_mfma_f32_16x16x32_bf16 v[68:71], v[76:79], v[184:187], v[68:71]
	s_waitcnt lgkmcnt(4)
	v_mfma_f32_16x16x32_bf16 v[184:187], v[76:79], v[200:203], v[196:199]
	v_mfma_f32_16x16x32_bf16 v[68:71], v[164:167], v[188:191], v[68:71]
	s_waitcnt lgkmcnt(2)
	v_mfma_f32_16x16x32_bf16 v[184:187], v[164:167], v[204:207], v[184:187]
	v_mfma_f32_16x16x32_bf16 v[188:191], v[220:223], v[192:195], v[68:71]
	s_waitcnt lgkmcnt(0)
	v_mfma_f32_16x16x32_bf16 v[68:71], v[220:223], v[216:219], v[184:187]
	v_add_u32_e32 v152, 0x2000, v0
	v_add_u32_e32 v0, 0x3000, v0
	s_nop 2
	ds_read_b64 v[184:185], v152 offset:512
	ds_read_b64 v[186:187], v152 offset:544
	ds_read_b64 v[192:193], v152 offset:576
	ds_read_b64 v[194:195], v152 offset:608
	ds_read_b64 v[196:197], v152 offset:640
	ds_read_b64 v[198:199], v152 offset:672
	ds_read_b64 v[200:201], v152 offset:704
	ds_read_b64 v[202:203], v152 offset:736
	ds_read_b64 v[204:205], v0 offset:768
	ds_read_b64 v[206:207], v0 offset:800
	ds_read_b64 v[216:217], v0 offset:832
	ds_read_b64 v[218:219], v0 offset:864
	ds_read_b64 v[224:225], v0 offset:896
	ds_read_b64 v[226:227], v0 offset:928
	s_waitcnt lgkmcnt(12)
	ds_read_b64 v[228:229], v0 offset:960
	ds_read_b64 v[230:231], v0 offset:992
	v_mfma_f32_16x16x32_bf16 v[184:187], v[72:75], v[184:187], 0
	s_waitcnt lgkmcnt(6)
	v_mfma_f32_16x16x32_bf16 v[72:75], v[72:75], v[204:207], 0
	v_mfma_f32_16x16x32_bf16 v[184:187], v[76:79], v[192:195], v[184:187]
	s_waitcnt lgkmcnt(4)
	v_mfma_f32_16x16x32_bf16 v[72:75], v[76:79], v[216:219], v[72:75]
	v_mfma_f32_16x16x32_bf16 v[76:79], v[164:167], v[196:199], v[184:187]
	s_waitcnt lgkmcnt(2)
	v_mfma_f32_16x16x32_bf16 v[72:75], v[164:167], v[224:227], v[72:75]
	v_mfma_f32_16x16x32_bf16 v[76:79], v[220:223], v[200:203], v[76:79]
	s_waitcnt lgkmcnt(0)
	v_mfma_f32_16x16x32_bf16 v[72:75], v[220:223], v[228:231], v[72:75]
	s_mul_i32 s16, s19, 0x4800
	v_add_u32_e32 v0, s16, v170
	v_add3_u32 v152, v172, s16, v181
	ds_read_b128 v[164:167], v0
	ds_read_b128 v[184:187], v0 offset:64
	v_lshl_add_u32 v0, s19, 9, v171
	ds_read_b128 v[192:195], v152 offset:34816
	ds_read_b128 v[196:199], v152 offset:34880
	ds_read_b128 v[200:203], v0
	ds_read_b128 v[204:207], v0 offset:64
	ds_read_b128 v[216:219], v152 offset:37120
	ds_read_b128 v[220:223], v152 offset:37184
	ds_read_b128 v[224:227], v152 offset:39424
	ds_read_b128 v[228:231], v152 offset:39488
	ds_read_b128 v[232:235], v0 offset:128
	ds_read_b128 v[236:239], v0 offset:192
	ds_read_b128 v[240:243], v152 offset:41728
	ds_read_b128 v[244:247], v152 offset:41792
	s_waitcnt lgkmcnt(9)
; #define MFMA16(a, b, c) __builtin_amdgcn_mfma_f32_16x16x32_bf16((a), (b), (c), 0, 0, 0)
; __device__ __forceinline__ void hgrn_b(unsigned char* lds, const Params& p, int jl, const bf16_t* proj, bf16_t* mix, const float* dbuf, const bf16_t* scr, const float* useg, const float* dseg, int blk, int G, int tid) {
;     ...
;                   __builtin_amdgcn_sched_barrier(0);
; #pragma unroll
;                   for (int k3 = 0; k3 < 4; ++k3) S[kh2 * 4 + k3] = S[kh2 * 4 + k3] * dv[k3];
; #pragma unroll
;                   for (int ks = 0; ks < 2; ++ks)
; #pragma unroll
;                       for (int k3 = 0; k3 < 4; ++k3) S[kh2 * 4 + k3] = MFMA16(kf[k3][ks], vb[ks], S[kh2 * 4 + k3]);
;                   __builtin_amdgcn_sched_barrier(0); } }
; #pragma unroll
;             for (int tt = 0; tt < 4; ++tt) { float ss = 0.f;
; #pragma unroll
;                 for (int j = 0; j < 4; ++j) { const unsigned wv = oin[tt][j >> 1]; const float oi = __uint_as_float((j & 1) ? (wv & 0xffff0000u) : (wv << 16)); const float ov = oT[tt][j] + oi; oT[tt][j] = ov; ss += ov * ov; }
;                 ss += __shfl_xor(ss, 16); ss += __shfl_xor(ss, 32);
;                 if (fq == 0) PART[(tt * 16 + fr) * 8 + w] = ss; }
	v_mul_f32_e32 v36, v36, v200
	v_mul_f32_e32 v37, v37, v201
	v_mul_f32_e32 v38, v38, v202
	v_mul_f32_e32 v39, v39, v203
	s_waitcnt lgkmcnt(8)
	v_mul_f32_e32 v40, v40, v204
	v_mul_f32_e32 v41, v41, v205
	v_mul_f32_e32 v42, v42, v206
	v_mul_f32_e32 v43, v43, v207
	s_waitcnt lgkmcnt(3)
	v_mul_f32_e32 v44, v44, v232
	v_mul_f32_e32 v45, v45, v233
	v_mul_f32_e32 v46, v46, v234
	v_mul_f32_e32 v47, v47, v235
	s_waitcnt lgkmcnt(2)
	v_mul_f32_e32 v48, v48, v236
	v_mul_f32_e32 v49, v49, v237
	v_mul_f32_e32 v50, v50, v238
	v_mul_f32_e32 v51, v51, v239
	v_mfma_f32_16x16x32_bf16 v[36:39], v[192:195], v[164:167], v[36:39]
	v_mfma_f32_16x16x32_bf16 v[40:43], v[216:219], v[164:167], v[40:43]
	v_mfma_f32_16x16x32_bf16 v[44:47], v[224:227], v[164:167], v[44:47]
	s_waitcnt lgkmcnt(1)
	v_mfma_f32_16x16x32_bf16 v[48:51], v[240:243], v[164:167], v[48:51]
	v_mfma_f32_16x16x32_bf16 v[36:39], v[196:199], v[184:187], v[36:39]
	v_mfma_f32_16x16x32_bf16 v[40:43], v[220:223], v[184:187], v[40:43]
	v_mfma_f32_16x16x32_bf16 v[44:47], v[228:231], v[184:187], v[44:47]
	s_waitcnt lgkmcnt(0)
	v_mfma_f32_16x16x32_bf16 v[48:51], v[244:247], v[184:187], v[48:51]
	ds_read_b128 v[192:195], v152 offset:44032
	ds_read_b128 v[196:199], v152 offset:44096
	ds_read_b128 v[200:203], v0 offset:256
	ds_read_b128 v[204:207], v0 offset:320
	ds_read_b128 v[216:219], v152 offset:46336
	ds_read_b128 v[220:223], v152 offset:46400
	ds_read_b128 v[224:227], v152 offset:48640
	ds_read_b128 v[228:231], v152 offset:48704
	ds_read_b128 v[232:235], v0 offset:384
	ds_read_b128 v[236:239], v0 offset:448
	ds_read_b128 v[240:243], v152 offset:50944
	ds_read_b128 v[244:247], v152 offset:51008
	s_waitcnt lgkmcnt(9)
	v_mul_f32_e32 v52, v52, v200
	v_mul_f32_e32 v53, v53, v201
	v_mul_f32_e32 v54, v54, v202
	v_mul_f32_e32 v55, v55, v203
	s_waitcnt lgkmcnt(8)
	v_mul_f32_e32 v56, v56, v204
	v_mul_f32_e32 v57, v57, v205
	v_mul_f32_e32 v58, v58, v206
	v_mul_f32_e32 v59, v59, v207
	s_waitcnt lgkmcnt(3)
	v_mul_f32_e32 v60, v60, v232
	v_mul_f32_e32 v61, v61, v233
	v_mul_f32_e32 v62, v62, v234
	v_mul_f32_e32 v63, v63, v235
	s_waitcnt lgkmcnt(2)
	v_mul_f32_e32 v64, v64, v236
	v_mul_f32_e32 v65, v65, v237
	v_mul_f32_e32 v66, v66, v238
	v_mul_f32_e32 v67, v67, v239
	v_mfma_f32_16x16x32_bf16 v[52:55], v[192:195], v[164:167], v[52:55]
	v_mfma_f32_16x16x32_bf16 v[56:59], v[216:219], v[164:167], v[56:59]
	v_mfma_f32_16x16x32_bf16 v[60:63], v[224:227], v[164:167], v[60:63]
	s_waitcnt lgkmcnt(1)
	v_mfma_f32_16x16x32_bf16 v[64:67], v[240:243], v[164:167], v[64:67]
	v_mfma_f32_16x16x32_bf16 v[52:55], v[196:199], v[184:187], v[52:55]
	v_mfma_f32_16x16x32_bf16 v[56:59], v[220:223], v[184:187], v[56:59]
	v_mfma_f32_16x16x32_bf16 v[60:63], v[228:231], v[184:187], v[60:63]
	s_waitcnt lgkmcnt(0)
	v_mfma_f32_16x16x32_bf16 v[64:67], v[244:247], v[184:187], v[64:67]
	s_waitcnt vmcnt(3)
	v_lshlrev_b32_e32 v152, 16, v162
	v_and_b32_e32 v153, 0xffff0000, v162
	v_pk_add_f32 v[166:167], v[188:189], v[152:153]
	v_lshlrev_b32_e32 v162, 16, v163
	v_and_b32_e32 v163, 0xffff0000, v163
	v_pk_mul_f32 v[152:153], v[166:167], v[166:167]
	v_pk_add_f32 v[168:169], v[190:191], v[162:163]
	v_add_f32_e32 v0, v152, v153
	v_pk_mul_f32 v[162:163], v[168:169], v[168:169]
	s_nop 0
	v_add_f32_e32 v0, v162, v0
	v_add_f32_e32 v0, v163, v0
	v_mov_b32_e32 v152, v0
	s_nop 1
	v_permlane16_swap_b32_e32 v152, v0
	v_add_f32_e32 v0, v0, v152
	v_mov_b32_e32 v162, v0
	s_nop 1
	v_permlane32_swap_b32_e32 v162, v0
	v_add_f32_e32 v0, v0, v162
	s_and_saveexec_b64 s[16:17], s[4:5]
	s_cbranch_execz .LBB0_414
	ds_write_b32 v176, v0
